# attention: gathered latent rows go global->LDS by LDS-DMA into an unpadded XOR-swizzled image (no VGPR staging, no ds_write_b128); row addresses and key indices of the next sub-block computed under PV
# baseline (speedup 1.0000x reference)
.LBB0_135:
	s_and_b32 s0, s76, 0x7ffff000
	s_mov_b32 s1, s77
	s_lshl_b64 s[0:1], s[0:1], 9
	v_mov_b32_e32 v72, 0
	s_and_b32 s29, s76, 0xfff
	v_mad_u64_u32 v[106:107], s[2:3], s76, v188, v[100:101]
	v_lshl_add_u64 v[108:109], v[102:103], 0, s[0:1]
	v_mov_b32_e32 v128, 0xff800000
	global_load_dwordx4 v[196:199], v[106:107], off
	global_load_dwordx4 v[200:203], v[106:107], off offset:64
	global_load_dwordx4 v[204:207], v[106:107], off offset:128
	global_load_dwordx4 v[208:211], v[106:107], off offset:192
	global_load_dwordx4 v[212:215], v[106:107], off offset:256
	global_load_dwordx4 v[216:219], v[106:107], off offset:320
	global_load_dwordx4 v[220:223], v[106:107], off offset:384
	global_load_dwordx4 v[224:227], v[106:107], off offset:448
	s_mov_b32 s30, 0
	v_mov_b32_e32 v68, 0
	v_mov_b32_e32 v69, v72
	v_mov_b32_e32 v70, v72
	v_mov_b32_e32 v71, v72
	v_mov_b32_e32 v24, 0
	v_mov_b32_e32 v25, v72
	v_mov_b32_e32 v26, v72
	v_mov_b32_e32 v27, v72
	v_mov_b32_e32 v64, 0
	v_mov_b32_e32 v65, v72
	v_mov_b32_e32 v66, v72
	v_mov_b32_e32 v67, v72
	v_mov_b32_e32 v60, 0
	v_mov_b32_e32 v61, v72
	v_mov_b32_e32 v62, v72
	v_mov_b32_e32 v63, v72
	v_mov_b32_e32 v56, 0
	v_mov_b32_e32 v57, v72
	v_mov_b32_e32 v58, v72
	v_mov_b32_e32 v59, v72
	v_mov_b32_e32 v52, 0
	v_mov_b32_e32 v53, v72
	v_mov_b32_e32 v54, v72
	v_mov_b32_e32 v55, v72
	v_mov_b32_e32 v48, 0
	v_mov_b32_e32 v49, v72
	v_mov_b32_e32 v50, v72
	v_mov_b32_e32 v51, v72
	v_mov_b32_e32 v44, 0
	v_mov_b32_e32 v45, v72
	v_mov_b32_e32 v46, v72
	v_mov_b32_e32 v47, v72
	v_mov_b32_e32 v40, 0
	v_mov_b32_e32 v41, v72
	v_mov_b32_e32 v42, v72
	v_mov_b32_e32 v43, v72
	v_mov_b32_e32 v28, 0
	v_mov_b32_e32 v29, v72
	v_mov_b32_e32 v30, v72
	v_mov_b32_e32 v31, v72
	v_mov_b32_e32 v20, 0
	v_mov_b32_e32 v21, v72
	v_mov_b32_e32 v22, v72
	v_mov_b32_e32 v23, v72
	v_mov_b32_e32 v16, 0
	v_mov_b32_e32 v17, v72
	v_mov_b32_e32 v18, v72
	v_mov_b32_e32 v19, v72
	v_mov_b32_e32 v12, 0
	v_mov_b32_e32 v13, v72
	v_mov_b32_e32 v14, v72
	v_mov_b32_e32 v15, v72
	v_mov_b32_e32 v8, 0
	v_mov_b32_e32 v9, v72
	v_mov_b32_e32 v10, v72
	v_mov_b32_e32 v11, v72
	v_mov_b32_e32 v4, 0
	v_mov_b32_e32 v5, v72
	v_mov_b32_e32 v6, v72
	v_mov_b32_e32 v7, v72
	v_mov_b32_e32 v0, 0
	v_mov_b32_e32 v1, v72
	v_mov_b32_e32 v2, v72
	v_mov_b32_e32 v3, v72
	v_and_b32_e32 v132, 63, v165
	v_and_b32_e32 v133, 15, v132
	v_lshrrev_b32_e32 v134, 4, v132
	v_and_b32_e32 v135, 7, v133
	v_lshlrev_b32_e32 v135, 1, v135
	s_lshl_b32 s0, s22, 14
	v_lshl_add_u32 v136, v133, 9, s0
	v_add_u32_e32 v137, 0, v134
	v_xor_b32_e32 v137, v137, v135
	v_lshl_add_u32 v88, v137, 4, v136
	v_add_u32_e32 v137, 4, v134
	v_xor_b32_e32 v137, v137, v135
	v_lshl_add_u32 v89, v137, 4, v136
	v_add_u32_e32 v137, 8, v134
	v_xor_b32_e32 v137, v137, v135
	v_lshl_add_u32 v90, v137, 4, v136
	v_add_u32_e32 v137, 12, v134
	v_xor_b32_e32 v137, v137, v135
	v_lshl_add_u32 v91, v137, 4, v136
	v_lshrrev_b32_e32 v137, 2, v133
	v_lshl_add_u32 v137, v134, 2, v137
	v_and_b32_e32 v138, 7, v137
	v_lshl_add_u32 v139, v137, 9, s0
	v_bfe_u32 v140, v133, 1, 1
	v_and_b32_e32 v141, 1, v133
	v_lshl_add_u32 v139, v141, 3, v139
	v_lshl_add_u32 v139, v140, 4, v139
	v_xor_b32_e32 v137, 0, v138
	v_lshl_add_u32 v92, v137, 5, v139
	v_xor_b32_e32 v137, 1, v138
	v_lshl_add_u32 v93, v137, 5, v139
	v_xor_b32_e32 v137, 2, v138
	v_lshl_add_u32 v94, v137, 5, v139
	v_xor_b32_e32 v137, 3, v138
	v_lshl_add_u32 v95, v137, 5, v139
	v_xor_b32_e32 v137, 4, v138
	v_lshl_add_u32 v96, v137, 5, v139
	v_xor_b32_e32 v137, 5, v138
	v_lshl_add_u32 v97, v137, 5, v139
	v_xor_b32_e32 v137, 6, v138
	v_lshl_add_u32 v98, v137, 5, v139
	v_xor_b32_e32 v137, 7, v138
	v_lshl_add_u32 v99, v137, 5, v139
	v_and_b32_e32 v137, 31, v132
	v_add_u32_e32 v138, 0, v115
	v_and_b32_e32 v138, 7, v138
	v_lshlrev_b32_e32 v138, 1, v138
	v_xor_b32_e32 v138, v138, v137
	v_lshlrev_b32_e32 v152, 4, v138
	v_add_u32_e32 v138, 2, v115
	v_and_b32_e32 v138, 7, v138
	v_lshlrev_b32_e32 v138, 1, v138
	v_xor_b32_e32 v138, v138, v137
	v_lshlrev_b32_e32 v153, 4, v138
	v_add_u32_e32 v138, 4, v115
	v_and_b32_e32 v138, 7, v138
	v_lshlrev_b32_e32 v138, 1, v138
	v_xor_b32_e32 v138, v138, v137
	v_lshlrev_b32_e32 v154, 4, v138
	v_add_u32_e32 v138, 6, v115
	v_and_b32_e32 v138, 7, v138
	v_lshlrev_b32_e32 v138, 1, v138
	v_xor_b32_e32 v138, v138, v137
	v_lshlrev_b32_e32 v155, 4, v138
	v_mov_b32_e32 v244, v124
	s_nop 1
	v_readlane_b32 s0, v244, 0
	v_readlane_b32 s1, v244, 1
	v_readlane_b32 vcc_lo, v244, 2
	v_readlane_b32 vcc_hi, v244, 3
	s_mov_b32 exec_lo, 0xffff
	s_mov_b32 exec_hi, 0x0
	v_mov_b32_e32 v164, s0
	v_mov_b32_e32 v166, s1
	v_mov_b32_e32 v168, vcc_lo
	v_mov_b32_e32 v169, vcc_hi
	s_mov_b64 exec, -1
	s_max_i32 s0, s0, 0
	s_max_i32 s1, s1, 0
	s_max_i32 vcc_lo, vcc_lo, 0
	s_max_i32 vcc_hi, vcc_hi, 0
	s_sub_i32 s1, s1, s0
	s_sub_i32 vcc_hi, vcc_hi, vcc_lo
	s_lshl_b32 s0, s0, 9
	s_lshl_b32 s1, s1, 9
	s_lshl_b32 vcc_lo, vcc_lo, 9
	s_lshl_b32 vcc_hi, vcc_hi, 9
	v_add_u32_e32 v156, s0, v152
	v_add_u32_e32 v157, vcc_lo, v153
	v_mad_i32_i24 v156, v115, s1, v156
	v_mad_i32_i24 v157, v115, vcc_hi, v157
	v_readlane_b32 s0, v244, 4
	v_readlane_b32 s1, v244, 5
	v_readlane_b32 vcc_lo, v244, 6
	v_readlane_b32 vcc_hi, v244, 7
	s_mov_b32 exec_lo, 0xffff0000
	s_mov_b32 exec_hi, 0x0
	v_mov_b32_e32 v164, s0
	v_mov_b32_e32 v166, s1
	v_mov_b32_e32 v168, vcc_lo
	v_mov_b32_e32 v169, vcc_hi
	s_mov_b64 exec, -1
	s_max_i32 s0, s0, 0
	s_max_i32 s1, s1, 0
	s_max_i32 vcc_lo, vcc_lo, 0
	s_max_i32 vcc_hi, vcc_hi, 0
	s_sub_i32 s1, s1, s0
	s_sub_i32 vcc_hi, vcc_hi, vcc_lo
	s_lshl_b32 s0, s0, 9
	s_lshl_b32 s1, s1, 9
	s_lshl_b32 vcc_lo, vcc_lo, 9
	s_lshl_b32 vcc_hi, vcc_hi, 9
	v_add_u32_e32 v158, s0, v154
	v_add_u32_e32 v159, vcc_lo, v155
	v_mad_i32_i24 v158, v115, s1, v158
	v_mad_i32_i24 v159, v115, vcc_hi, v159
	v_readlane_b32 s0, v244, 8
	v_readlane_b32 s1, v244, 9
	v_readlane_b32 vcc_lo, v244, 10
	v_readlane_b32 vcc_hi, v244, 11
	s_mov_b32 exec_lo, 0x0
	s_mov_b32 exec_hi, 0xffff
	v_mov_b32_e32 v164, s0
	v_mov_b32_e32 v166, s1
	v_mov_b32_e32 v168, vcc_lo
	v_mov_b32_e32 v169, vcc_hi
	s_mov_b64 exec, -1
	s_max_i32 s0, s0, 0
	s_max_i32 s1, s1, 0
	s_max_i32 vcc_lo, vcc_lo, 0
	s_max_i32 vcc_hi, vcc_hi, 0
	s_sub_i32 s1, s1, s0
	s_sub_i32 vcc_hi, vcc_hi, vcc_lo
	s_lshl_b32 s0, s0, 9
	s_lshl_b32 s1, s1, 9
	s_lshl_b32 vcc_lo, vcc_lo, 9
	s_lshl_b32 vcc_hi, vcc_hi, 9
	v_add_u32_e32 v160, s0, v152
	v_add_u32_e32 v161, vcc_lo, v153
	v_mad_i32_i24 v160, v115, s1, v160
	v_mad_i32_i24 v161, v115, vcc_hi, v161
	v_readlane_b32 s0, v244, 12
	v_readlane_b32 s1, v244, 13
	v_readlane_b32 vcc_lo, v244, 14
	v_readlane_b32 vcc_hi, v244, 15
	s_mov_b32 exec_lo, 0x0
	s_mov_b32 exec_hi, 0xffff0000
	v_mov_b32_e32 v164, s0
	v_mov_b32_e32 v166, s1
	v_mov_b32_e32 v168, vcc_lo
	v_mov_b32_e32 v169, vcc_hi
	s_mov_b64 exec, -1
	s_max_i32 s0, s0, 0
	s_max_i32 s1, s1, 0
	s_max_i32 vcc_lo, vcc_lo, 0
	s_max_i32 vcc_hi, vcc_hi, 0
	s_sub_i32 s1, s1, s0
	s_sub_i32 vcc_hi, vcc_hi, vcc_lo
	s_lshl_b32 s0, s0, 9
	s_lshl_b32 s1, s1, 9
	s_lshl_b32 vcc_lo, vcc_lo, 9
	s_lshl_b32 vcc_hi, vcc_hi, 9
	v_add_u32_e32 v162, s0, v154
	v_add_u32_e32 v163, vcc_lo, v155
	v_mad_i32_i24 v162, v115, s1, v162
	v_mad_i32_i24 v163, v115, vcc_hi, v163
	v_readlane_b32 s0, v244, 16
	v_readlane_b32 s1, v244, 17
	v_readlane_b32 vcc_lo, v244, 18
	v_readlane_b32 vcc_hi, v244, 19
	s_mov_b32 exec_lo, 0xffff
	s_mov_b32 exec_hi, 0x0
	v_mov_b32_e32 v170, s0
	v_mov_b32_e32 v176, s1
	v_mov_b32_e32 v177, vcc_lo
	v_mov_b32_e32 v191, vcc_hi
	s_mov_b64 exec, -1
	s_max_i32 s0, s0, 0
	s_max_i32 s1, s1, 0
	s_max_i32 vcc_lo, vcc_lo, 0
	s_max_i32 vcc_hi, vcc_hi, 0
	s_sub_i32 s1, s1, s0
	s_sub_i32 vcc_hi, vcc_hi, vcc_lo
	s_lshl_b32 s0, s0, 9
	s_lshl_b32 s1, s1, 9
	s_lshl_b32 vcc_lo, vcc_lo, 9
	s_lshl_b32 vcc_hi, vcc_hi, 9
	v_add_u32_e32 v144, s0, v152
	v_add_u32_e32 v145, vcc_lo, v153
	v_mad_i32_i24 v144, v115, s1, v144
	v_mad_i32_i24 v145, v115, vcc_hi, v145
	v_readlane_b32 s0, v244, 20
	v_readlane_b32 s1, v244, 21
	v_readlane_b32 vcc_lo, v244, 22
	v_readlane_b32 vcc_hi, v244, 23
	s_mov_b32 exec_lo, 0xffff0000
	s_mov_b32 exec_hi, 0x0
	v_mov_b32_e32 v170, s0
	v_mov_b32_e32 v176, s1
	v_mov_b32_e32 v177, vcc_lo
	v_mov_b32_e32 v191, vcc_hi
	s_mov_b64 exec, -1
	s_max_i32 s0, s0, 0
	s_max_i32 s1, s1, 0
	s_max_i32 vcc_lo, vcc_lo, 0
	s_max_i32 vcc_hi, vcc_hi, 0
	s_sub_i32 s1, s1, s0
	s_sub_i32 vcc_hi, vcc_hi, vcc_lo
	s_lshl_b32 s0, s0, 9
	s_lshl_b32 s1, s1, 9
	s_lshl_b32 vcc_lo, vcc_lo, 9
	s_lshl_b32 vcc_hi, vcc_hi, 9
	v_add_u32_e32 v146, s0, v154
	v_add_u32_e32 v147, vcc_lo, v155
	v_mad_i32_i24 v146, v115, s1, v146
	v_mad_i32_i24 v147, v115, vcc_hi, v147
	v_readlane_b32 s0, v244, 24
	v_readlane_b32 s1, v244, 25
	v_readlane_b32 vcc_lo, v244, 26
	v_readlane_b32 vcc_hi, v244, 27
	s_mov_b32 exec_lo, 0x0
	s_mov_b32 exec_hi, 0xffff
	v_mov_b32_e32 v170, s0
	v_mov_b32_e32 v176, s1
	v_mov_b32_e32 v177, vcc_lo
	v_mov_b32_e32 v191, vcc_hi
	s_mov_b64 exec, -1
	s_max_i32 s0, s0, 0
	s_max_i32 s1, s1, 0
	s_max_i32 vcc_lo, vcc_lo, 0
	s_max_i32 vcc_hi, vcc_hi, 0
	s_sub_i32 s1, s1, s0
	s_sub_i32 vcc_hi, vcc_hi, vcc_lo
	s_lshl_b32 s0, s0, 9
	s_lshl_b32 s1, s1, 9
	s_lshl_b32 vcc_lo, vcc_lo, 9
	s_lshl_b32 vcc_hi, vcc_hi, 9
	v_add_u32_e32 v172, s0, v152
	v_add_u32_e32 v173, vcc_lo, v153
	v_mad_i32_i24 v172, v115, s1, v172
	v_mad_i32_i24 v173, v115, vcc_hi, v173
	v_readlane_b32 s0, v244, 28
	v_readlane_b32 s1, v244, 29
	v_readlane_b32 vcc_lo, v244, 30
	v_readlane_b32 vcc_hi, v244, 31
	s_mov_b32 exec_lo, 0x0
	s_mov_b32 exec_hi, 0xffff0000
	v_mov_b32_e32 v170, s0
	v_mov_b32_e32 v176, s1
	v_mov_b32_e32 v177, vcc_lo
	v_mov_b32_e32 v191, vcc_hi
	s_mov_b64 exec, -1
	s_max_i32 s0, s0, 0
	s_max_i32 s1, s1, 0
	s_max_i32 vcc_lo, vcc_lo, 0
	s_max_i32 vcc_hi, vcc_hi, 0
	s_sub_i32 s1, s1, s0
	s_sub_i32 vcc_hi, vcc_hi, vcc_lo
	s_lshl_b32 s0, s0, 9
	s_lshl_b32 s1, s1, 9
	s_lshl_b32 vcc_lo, vcc_lo, 9
	s_lshl_b32 vcc_hi, vcc_hi, 9
	v_add_u32_e32 v174, s0, v154
	v_add_u32_e32 v175, vcc_lo, v155
	v_mad_i32_i24 v174, v115, s1, v174
	v_mad_i32_i24 v175, v115, vcc_hi, v175
.LBB0_136:
	v_mov_b32_e32 v129, v72
	v_readfirstlane_b32 s2, v108
	v_readfirstlane_b32 s3, v109
	s_lshl_b32 m0, s22, 14
	s_nop 4
	s_nop 0
	global_load_lds_dwordx4 v156, s[2:3]
	s_add_i32 m0, m0, 0x400
	s_nop 0
	global_load_lds_dwordx4 v157, s[2:3]
	s_add_i32 m0, m0, 0x400
	s_nop 0
	global_load_lds_dwordx4 v158, s[2:3]
	s_add_i32 m0, m0, 0x400
	s_nop 0
	global_load_lds_dwordx4 v159, s[2:3]
	s_add_i32 m0, m0, 0x400
	s_nop 0
	global_load_lds_dwordx4 v160, s[2:3]
	s_add_i32 m0, m0, 0x400
	s_nop 0
	global_load_lds_dwordx4 v161, s[2:3]
	s_add_i32 m0, m0, 0x400
	s_nop 0
	global_load_lds_dwordx4 v162, s[2:3]
	s_add_i32 m0, m0, 0x400
	s_nop 0
	global_load_lds_dwordx4 v163, s[2:3]
	s_add_i32 m0, m0, 0x400
	s_nop 0
	global_load_lds_dwordx4 v144, s[2:3]
	s_add_i32 m0, m0, 0x400
	s_nop 0
	global_load_lds_dwordx4 v145, s[2:3]
	s_add_i32 m0, m0, 0x400
	s_nop 0
	global_load_lds_dwordx4 v146, s[2:3]
	s_add_i32 m0, m0, 0x400
	s_nop 0
	global_load_lds_dwordx4 v147, s[2:3]
	s_add_i32 m0, m0, 0x400
	s_nop 0
	global_load_lds_dwordx4 v172, s[2:3]
	s_add_i32 m0, m0, 0x400
	s_nop 0
	global_load_lds_dwordx4 v173, s[2:3]
	s_add_i32 m0, m0, 0x400
	s_nop 0
	global_load_lds_dwordx4 v174, s[2:3]
	s_add_i32 m0, m0, 0x400
	s_nop 0
	global_load_lds_dwordx4 v175, s[2:3]
	s_waitcnt vmcnt(0)
	s_waitcnt lgkmcnt(7)
	v_cmp_lt_i32_e32 vcc, -1, v164
	s_waitcnt lgkmcnt(0)
	ds_read_b128 v[228:231], v88
	ds_read_b128 v[232:235], v89
	ds_read_b128 v[236:239], v90
	ds_read_b128 v[240:243], v91
	s_waitcnt lgkmcnt(3)
	v_mfma_f32_16x16x32_bf16 v[134:137], v[228:231], v[196:199], 0
	ds_read_b128 v[228:231], v88 offset:256
	s_waitcnt lgkmcnt(3)
	v_mfma_f32_16x16x32_bf16 v[134:137], v[232:235], v[200:203], v[134:137]
	ds_read_b128 v[232:235], v89 offset:256
	s_waitcnt lgkmcnt(3)
	v_mfma_f32_16x16x32_bf16 v[134:137], v[236:239], v[204:207], v[134:137]
	ds_read_b128 v[236:239], v90 offset:256
	s_waitcnt lgkmcnt(3)
	v_mfma_f32_16x16x32_bf16 v[134:137], v[240:243], v[208:211], v[134:137]
	ds_read_b128 v[240:243], v91 offset:256
	s_waitcnt lgkmcnt(3)
	v_mfma_f32_16x16x32_bf16 v[134:137], v[228:231], v[212:215], v[134:137]
	ds_read_b128 v[228:231], v88 offset:8192
	s_waitcnt lgkmcnt(3)
	v_mfma_f32_16x16x32_bf16 v[134:137], v[232:235], v[216:219], v[134:137]
	ds_read_b128 v[232:235], v89 offset:8192
	s_waitcnt lgkmcnt(3)
	v_mfma_f32_16x16x32_bf16 v[134:137], v[236:239], v[220:223], v[134:137]
	ds_read_b128 v[236:239], v90 offset:8192
	s_waitcnt lgkmcnt(3)
	v_mfma_f32_16x16x32_bf16 v[134:137], v[240:243], v[224:227], v[134:137]
	ds_read_b128 v[240:243], v91 offset:8192
	s_waitcnt lgkmcnt(3)
	v_mfma_f32_16x16x32_bf16 v[72:75], v[228:231], v[196:199], 0
	ds_read_b128 v[228:231], v88 offset:8448
	s_waitcnt lgkmcnt(3)
	v_mfma_f32_16x16x32_bf16 v[72:75], v[232:235], v[200:203], v[72:75]
	ds_read_b128 v[232:235], v89 offset:8448
	s_waitcnt lgkmcnt(3)
	v_mfma_f32_16x16x32_bf16 v[72:75], v[236:239], v[204:207], v[72:75]
	ds_read_b128 v[236:239], v90 offset:8448
	s_waitcnt lgkmcnt(3)
	v_mfma_f32_16x16x32_bf16 v[72:75], v[240:243], v[208:211], v[72:75]
	ds_read_b128 v[240:243], v91 offset:8448
	v_subrev_u32_e32 v80, s29, v170
	v_med3_i32 v80, v80, s4, v189
	v_lshl_add_u32 v80, v80, 6, v116
	ds_read_b32 v80, v80 offset:8192
	s_waitcnt lgkmcnt(4)
	v_mfma_f32_16x16x32_bf16 v[72:75], v[228:231], v[212:215], v[72:75]
	s_waitcnt lgkmcnt(3)
	v_mfma_f32_16x16x32_bf16 v[72:75], v[232:235], v[216:219], v[72:75]
	s_waitcnt lgkmcnt(2)
	v_mfma_f32_16x16x32_bf16 v[72:75], v[236:239], v[220:223], v[72:75]
	s_waitcnt lgkmcnt(1)
	v_mfma_f32_16x16x32_bf16 v[72:75], v[240:243], v[224:227], v[72:75]
	v_subrev_u32_e32 v76, s29, v164
	v_med3_i32 v76, v76, s4, v189
	v_subrev_u32_e32 v77, s29, v166
	v_lshl_add_u32 v76, v76, 6, v116
	v_med3_i32 v77, v77, s4, v189
	v_subrev_u32_e32 v78, s29, v168
	ds_read_b32 v76, v76 offset:8192
	v_lshl_add_u32 v77, v77, 6, v116
	v_med3_i32 v78, v78, s4, v189
	v_subrev_u32_e32 v79, s29, v169
	ds_read_b32 v77, v77 offset:8192
	v_lshl_add_u32 v78, v78, 6, v116
	v_med3_i32 v79, v79, s4, v189
	ds_read_b32 v78, v78 offset:8192
	v_lshl_add_u32 v79, v79, 6, v116
	ds_read_b32 v79, v79 offset:8192
	s_waitcnt lgkmcnt(3)
	v_fmac_f32_e32 v76, 0x3d800000, v134
	v_cndmask_b32_e32 v76, v190, v76, vcc
	s_waitcnt lgkmcnt(2)
	v_fmac_f32_e32 v77, 0x3d800000, v135
	v_cmp_lt_i32_e32 vcc, -1, v166
	s_waitcnt lgkmcnt(1)
	v_fmac_f32_e32 v78, 0x3d800000, v136
	s_waitcnt lgkmcnt(0)
	v_fmac_f32_e32 v79, 0x3d800000, v137
	v_cndmask_b32_e32 v77, v190, v77, vcc
	v_cmp_lt_i32_e32 vcc, -1, v168
	v_fmac_f32_e32 v80, 0x3d800000, v72
	s_nop 0
	v_cndmask_b32_e32 v78, v190, v78, vcc
	v_cmp_lt_i32_e32 vcc, -1, v169
	s_nop 1
	v_cndmask_b32_e32 v79, v190, v79, vcc
	v_cmp_lt_i32_e32 vcc, -1, v170
	v_max_f32_e32 v81, v78, v79
	s_nop 0
	v_cndmask_b32_e32 v72, v190, v80, vcc
	v_subrev_u32_e32 v80, s29, v176
	v_med3_i32 v80, v80, s4, v189
	v_lshl_add_u32 v80, v80, 6, v116
	ds_read_b32 v80, v80 offset:8192
	v_cmp_lt_i32_e32 vcc, -1, v176
	s_waitcnt lgkmcnt(0)
	v_fmac_f32_e32 v80, 0x3d800000, v73
	v_subrev_u32_e32 v73, s29, v177
	v_med3_i32 v73, v73, s4, v189
	v_lshl_add_u32 v73, v73, 6, v116
	ds_read_b32 v73, v73 offset:8192
	v_cndmask_b32_e32 v80, v190, v80, vcc
	v_cmp_lt_i32_e32 vcc, -1, v177
	s_waitcnt lgkmcnt(0)
	v_fmac_f32_e32 v73, 0x3d800000, v74
	v_cndmask_b32_e32 v74, v190, v73, vcc
	v_subrev_u32_e32 v73, s29, v191
	v_med3_i32 v73, v73, s4, v189
	v_lshl_add_u32 v73, v73, 6, v116
	ds_read_b32 v73, v73 offset:8192
	v_cmp_lt_i32_e32 vcc, -1, v191
	s_waitcnt lgkmcnt(0)
	v_fmac_f32_e32 v73, 0x3d800000, v75
	v_cndmask_b32_e32 v75, v190, v73, vcc
	s_add_i32 s2, s30, 1
	s_cmp_eq_u32 s2, 8
	s_cbranch_scc1 .Latt_a_done
	s_lshr_b32 s3, s2, 1
	s_cmp_eq_u32 s3, 2
	s_cselect_b64 vcc, -1, 0
	v_cndmask_b32_e32 v244, v127, v126, vcc
	s_cmp_eq_u32 s3, 1
	s_cselect_b64 vcc, -1, 0
	v_cndmask_b32_e32 v244, v244, v125, vcc
	s_cmp_eq_u32 s3, 0
	s_cselect_b64 vcc, -1, 0
	v_cndmask_b32_e32 v244, v244, v124, vcc
	s_bitcmp1_b32 s2, 0
	s_cbranch_scc1 .Latt_a_odd
	v_readlane_b32 s0, v244, 0
	v_readlane_b32 s1, v244, 1
	v_readlane_b32 vcc_lo, v244, 2
	v_readlane_b32 vcc_hi, v244, 3
	s_mov_b32 exec_lo, 0xffff
	s_mov_b32 exec_hi, 0x0
	v_mov_b32_e32 v164, s0
	v_mov_b32_e32 v166, s1
	v_mov_b32_e32 v168, vcc_lo
	v_mov_b32_e32 v169, vcc_hi
	s_mov_b64 exec, -1
	s_max_i32 s0, s0, 0
	s_max_i32 s1, s1, 0
	s_max_i32 vcc_lo, vcc_lo, 0
	s_max_i32 vcc_hi, vcc_hi, 0
	s_sub_i32 s1, s1, s0
	s_sub_i32 vcc_hi, vcc_hi, vcc_lo
	s_lshl_b32 s0, s0, 9
	s_lshl_b32 s1, s1, 9
	s_lshl_b32 vcc_lo, vcc_lo, 9
	s_lshl_b32 vcc_hi, vcc_hi, 9
	v_add_u32_e32 v156, s0, v152
	v_add_u32_e32 v157, vcc_lo, v153
	v_mad_i32_i24 v156, v115, s1, v156
	v_mad_i32_i24 v157, v115, vcc_hi, v157
	v_readlane_b32 s0, v244, 4
	v_readlane_b32 s1, v244, 5
	v_readlane_b32 vcc_lo, v244, 6
	v_readlane_b32 vcc_hi, v244, 7
	s_mov_b32 exec_lo, 0xffff0000
	s_mov_b32 exec_hi, 0x0
	v_mov_b32_e32 v164, s0
	v_mov_b32_e32 v166, s1
	v_mov_b32_e32 v168, vcc_lo
	v_mov_b32_e32 v169, vcc_hi
	s_mov_b64 exec, -1
	s_max_i32 s0, s0, 0
	s_max_i32 s1, s1, 0
	s_max_i32 vcc_lo, vcc_lo, 0
	s_max_i32 vcc_hi, vcc_hi, 0
	s_sub_i32 s1, s1, s0
	s_sub_i32 vcc_hi, vcc_hi, vcc_lo
	s_lshl_b32 s0, s0, 9
	s_lshl_b32 s1, s1, 9
	s_lshl_b32 vcc_lo, vcc_lo, 9
	s_lshl_b32 vcc_hi, vcc_hi, 9
	v_add_u32_e32 v158, s0, v154
	v_add_u32_e32 v159, vcc_lo, v155
	v_mad_i32_i24 v158, v115, s1, v158
	v_mad_i32_i24 v159, v115, vcc_hi, v159
	v_readlane_b32 s0, v244, 8
	v_readlane_b32 s1, v244, 9
	v_readlane_b32 vcc_lo, v244, 10
	v_readlane_b32 vcc_hi, v244, 11
	s_mov_b32 exec_lo, 0x0
	s_mov_b32 exec_hi, 0xffff
	v_mov_b32_e32 v164, s0
	v_mov_b32_e32 v166, s1
	v_mov_b32_e32 v168, vcc_lo
	v_mov_b32_e32 v169, vcc_hi
	s_mov_b64 exec, -1
	s_max_i32 s0, s0, 0
	s_max_i32 s1, s1, 0
	s_max_i32 vcc_lo, vcc_lo, 0
	s_max_i32 vcc_hi, vcc_hi, 0
	s_sub_i32 s1, s1, s0
	s_sub_i32 vcc_hi, vcc_hi, vcc_lo
	s_lshl_b32 s0, s0, 9
	s_lshl_b32 s1, s1, 9
	s_lshl_b32 vcc_lo, vcc_lo, 9
	s_lshl_b32 vcc_hi, vcc_hi, 9
	v_add_u32_e32 v160, s0, v152
	v_add_u32_e32 v161, vcc_lo, v153
	v_mad_i32_i24 v160, v115, s1, v160
	v_mad_i32_i24 v161, v115, vcc_hi, v161
	v_readlane_b32 s0, v244, 12
	v_readlane_b32 s1, v244, 13
	v_readlane_b32 vcc_lo, v244, 14
	v_readlane_b32 vcc_hi, v244, 15
	s_mov_b32 exec_lo, 0x0
	s_mov_b32 exec_hi, 0xffff0000
	v_mov_b32_e32 v164, s0
	v_mov_b32_e32 v166, s1
	v_mov_b32_e32 v168, vcc_lo
	v_mov_b32_e32 v169, vcc_hi
	s_mov_b64 exec, -1
	s_max_i32 s0, s0, 0
	s_max_i32 s1, s1, 0
	s_max_i32 vcc_lo, vcc_lo, 0
	s_max_i32 vcc_hi, vcc_hi, 0
	s_sub_i32 s1, s1, s0
	s_sub_i32 vcc_hi, vcc_hi, vcc_lo
	s_lshl_b32 s0, s0, 9
	s_lshl_b32 s1, s1, 9
	s_lshl_b32 vcc_lo, vcc_lo, 9
	s_lshl_b32 vcc_hi, vcc_hi, 9
	v_add_u32_e32 v162, s0, v154
	v_add_u32_e32 v163, vcc_lo, v155
	v_mad_i32_i24 v162, v115, s1, v162
	v_mad_i32_i24 v163, v115, vcc_hi, v163
	v_readlane_b32 s0, v244, 16
	v_readlane_b32 s1, v244, 17
	v_readlane_b32 vcc_lo, v244, 18
	v_readlane_b32 vcc_hi, v244, 19
	s_mov_b32 exec_lo, 0xffff
	s_mov_b32 exec_hi, 0x0
	v_mov_b32_e32 v170, s0
	v_mov_b32_e32 v176, s1
	v_mov_b32_e32 v177, vcc_lo
	v_mov_b32_e32 v191, vcc_hi
	s_mov_b64 exec, -1
	s_max_i32 s0, s0, 0
	s_max_i32 s1, s1, 0
	s_max_i32 vcc_lo, vcc_lo, 0
	s_max_i32 vcc_hi, vcc_hi, 0
	s_sub_i32 s1, s1, s0
	s_sub_i32 vcc_hi, vcc_hi, vcc_lo
	s_lshl_b32 s0, s0, 9
	s_lshl_b32 s1, s1, 9
	s_lshl_b32 vcc_lo, vcc_lo, 9
	s_lshl_b32 vcc_hi, vcc_hi, 9
	v_add_u32_e32 v144, s0, v152
	v_add_u32_e32 v145, vcc_lo, v153
	v_mad_i32_i24 v144, v115, s1, v144
	v_mad_i32_i24 v145, v115, vcc_hi, v145
	v_readlane_b32 s0, v244, 20
	v_readlane_b32 s1, v244, 21
	v_readlane_b32 vcc_lo, v244, 22
	v_readlane_b32 vcc_hi, v244, 23
	s_mov_b32 exec_lo, 0xffff0000
	s_mov_b32 exec_hi, 0x0
	v_mov_b32_e32 v170, s0
	v_mov_b32_e32 v176, s1
	v_mov_b32_e32 v177, vcc_lo
	v_mov_b32_e32 v191, vcc_hi
	s_mov_b64 exec, -1
	s_max_i32 s0, s0, 0
	s_max_i32 s1, s1, 0
	s_max_i32 vcc_lo, vcc_lo, 0
	s_max_i32 vcc_hi, vcc_hi, 0
	s_sub_i32 s1, s1, s0
	s_sub_i32 vcc_hi, vcc_hi, vcc_lo
	s_lshl_b32 s0, s0, 9
	s_lshl_b32 s1, s1, 9
	s_lshl_b32 vcc_lo, vcc_lo, 9
	s_lshl_b32 vcc_hi, vcc_hi, 9
	v_add_u32_e32 v146, s0, v154
	v_add_u32_e32 v147, vcc_lo, v155
	v_mad_i32_i24 v146, v115, s1, v146
	v_mad_i32_i24 v147, v115, vcc_hi, v147
	v_readlane_b32 s0, v244, 24
	v_readlane_b32 s1, v244, 25
	v_readlane_b32 vcc_lo, v244, 26
	v_readlane_b32 vcc_hi, v244, 27
	s_mov_b32 exec_lo, 0x0
	s_mov_b32 exec_hi, 0xffff
	v_mov_b32_e32 v170, s0
	v_mov_b32_e32 v176, s1
	v_mov_b32_e32 v177, vcc_lo
	v_mov_b32_e32 v191, vcc_hi
	s_mov_b64 exec, -1
	s_max_i32 s0, s0, 0
	s_max_i32 s1, s1, 0
	s_max_i32 vcc_lo, vcc_lo, 0
	s_max_i32 vcc_hi, vcc_hi, 0
	s_sub_i32 s1, s1, s0
	s_sub_i32 vcc_hi, vcc_hi, vcc_lo
	s_lshl_b32 s0, s0, 9
	s_lshl_b32 s1, s1, 9
	s_lshl_b32 vcc_lo, vcc_lo, 9
	s_lshl_b32 vcc_hi, vcc_hi, 9
	v_add_u32_e32 v172, s0, v152
	v_add_u32_e32 v173, vcc_lo, v153
	v_mad_i32_i24 v172, v115, s1, v172
	v_mad_i32_i24 v173, v115, vcc_hi, v173
	v_readlane_b32 s0, v244, 28
	v_readlane_b32 s1, v244, 29
	v_readlane_b32 vcc_lo, v244, 30
	v_readlane_b32 vcc_hi, v244, 31
	s_mov_b32 exec_lo, 0x0
	s_mov_b32 exec_hi, 0xffff0000
	v_mov_b32_e32 v170, s0
	v_mov_b32_e32 v176, s1
	v_mov_b32_e32 v177, vcc_lo
	v_mov_b32_e32 v191, vcc_hi
	s_mov_b64 exec, -1
	s_max_i32 s0, s0, 0
	s_max_i32 s1, s1, 0
	s_max_i32 vcc_lo, vcc_lo, 0
	s_max_i32 vcc_hi, vcc_hi, 0
	s_sub_i32 s1, s1, s0
	s_sub_i32 vcc_hi, vcc_hi, vcc_lo
	s_lshl_b32 s0, s0, 9
	s_lshl_b32 s1, s1, 9
	s_lshl_b32 vcc_lo, vcc_lo, 9
	s_lshl_b32 vcc_hi, vcc_hi, 9
	v_add_u32_e32 v174, s0, v154
	v_add_u32_e32 v175, vcc_lo, v155
	v_mad_i32_i24 v174, v115, s1, v174
	v_mad_i32_i24 v175, v115, vcc_hi, v175
	s_branch .Latt_a_done
.Latt_a_odd:
	v_readlane_b32 s0, v244, 32
	v_readlane_b32 s1, v244, 33
	v_readlane_b32 vcc_lo, v244, 34
	v_readlane_b32 vcc_hi, v244, 35
	s_mov_b32 exec_lo, 0xffff
	s_mov_b32 exec_hi, 0x0
	v_mov_b32_e32 v164, s0
	v_mov_b32_e32 v166, s1
	v_mov_b32_e32 v168, vcc_lo
	v_mov_b32_e32 v169, vcc_hi
	s_mov_b64 exec, -1
	s_max_i32 s0, s0, 0
	s_max_i32 s1, s1, 0
	s_max_i32 vcc_lo, vcc_lo, 0
	s_max_i32 vcc_hi, vcc_hi, 0
	s_sub_i32 s1, s1, s0
	s_sub_i32 vcc_hi, vcc_hi, vcc_lo
	s_lshl_b32 s0, s0, 9
	s_lshl_b32 s1, s1, 9
	s_lshl_b32 vcc_lo, vcc_lo, 9
	s_lshl_b32 vcc_hi, vcc_hi, 9
	v_add_u32_e32 v156, s0, v152
	v_add_u32_e32 v157, vcc_lo, v153
	v_mad_i32_i24 v156, v115, s1, v156
	v_mad_i32_i24 v157, v115, vcc_hi, v157
	v_readlane_b32 s0, v244, 36
	v_readlane_b32 s1, v244, 37
	v_readlane_b32 vcc_lo, v244, 38
	v_readlane_b32 vcc_hi, v244, 39
	s_mov_b32 exec_lo, 0xffff0000
	s_mov_b32 exec_hi, 0x0
	v_mov_b32_e32 v164, s0
	v_mov_b32_e32 v166, s1
	v_mov_b32_e32 v168, vcc_lo
	v_mov_b32_e32 v169, vcc_hi
	s_mov_b64 exec, -1
	s_max_i32 s0, s0, 0
	s_max_i32 s1, s1, 0
	s_max_i32 vcc_lo, vcc_lo, 0
	s_max_i32 vcc_hi, vcc_hi, 0
	s_sub_i32 s1, s1, s0
	s_sub_i32 vcc_hi, vcc_hi, vcc_lo
	s_lshl_b32 s0, s0, 9
	s_lshl_b32 s1, s1, 9
	s_lshl_b32 vcc_lo, vcc_lo, 9
	s_lshl_b32 vcc_hi, vcc_hi, 9
	v_add_u32_e32 v158, s0, v154
	v_add_u32_e32 v159, vcc_lo, v155
	v_mad_i32_i24 v158, v115, s1, v158
	v_mad_i32_i24 v159, v115, vcc_hi, v159
	v_readlane_b32 s0, v244, 40
	v_readlane_b32 s1, v244, 41
	v_readlane_b32 vcc_lo, v244, 42
	v_readlane_b32 vcc_hi, v244, 43
	s_mov_b32 exec_lo, 0x0
	s_mov_b32 exec_hi, 0xffff
	v_mov_b32_e32 v164, s0
	v_mov_b32_e32 v166, s1
	v_mov_b32_e32 v168, vcc_lo
	v_mov_b32_e32 v169, vcc_hi
	s_mov_b64 exec, -1
	s_max_i32 s0, s0, 0
	s_max_i32 s1, s1, 0
	s_max_i32 vcc_lo, vcc_lo, 0
	s_max_i32 vcc_hi, vcc_hi, 0
	s_sub_i32 s1, s1, s0
	s_sub_i32 vcc_hi, vcc_hi, vcc_lo
	s_lshl_b32 s0, s0, 9
	s_lshl_b32 s1, s1, 9
	s_lshl_b32 vcc_lo, vcc_lo, 9
	s_lshl_b32 vcc_hi, vcc_hi, 9
	v_add_u32_e32 v160, s0, v152
	v_add_u32_e32 v161, vcc_lo, v153
	v_mad_i32_i24 v160, v115, s1, v160
	v_mad_i32_i24 v161, v115, vcc_hi, v161
	v_readlane_b32 s0, v244, 44
	v_readlane_b32 s1, v244, 45
	v_readlane_b32 vcc_lo, v244, 46
	v_readlane_b32 vcc_hi, v244, 47
	s_mov_b32 exec_lo, 0x0
	s_mov_b32 exec_hi, 0xffff0000
	v_mov_b32_e32 v164, s0
	v_mov_b32_e32 v166, s1
	v_mov_b32_e32 v168, vcc_lo
	v_mov_b32_e32 v169, vcc_hi
	s_mov_b64 exec, -1
	s_max_i32 s0, s0, 0
	s_max_i32 s1, s1, 0
	s_max_i32 vcc_lo, vcc_lo, 0
	s_max_i32 vcc_hi, vcc_hi, 0
	s_sub_i32 s1, s1, s0
	s_sub_i32 vcc_hi, vcc_hi, vcc_lo
	s_lshl_b32 s0, s0, 9
	s_lshl_b32 s1, s1, 9
	s_lshl_b32 vcc_lo, vcc_lo, 9
	s_lshl_b32 vcc_hi, vcc_hi, 9
	v_add_u32_e32 v162, s0, v154
	v_add_u32_e32 v163, vcc_lo, v155
	v_mad_i32_i24 v162, v115, s1, v162
	v_mad_i32_i24 v163, v115, vcc_hi, v163
	v_readlane_b32 s0, v244, 48
	v_readlane_b32 s1, v244, 49
	v_readlane_b32 vcc_lo, v244, 50
	v_readlane_b32 vcc_hi, v244, 51
	s_mov_b32 exec_lo, 0xffff
	s_mov_b32 exec_hi, 0x0
	v_mov_b32_e32 v170, s0
	v_mov_b32_e32 v176, s1
	v_mov_b32_e32 v177, vcc_lo
	v_mov_b32_e32 v191, vcc_hi
	s_mov_b64 exec, -1
	s_max_i32 s0, s0, 0
	s_max_i32 s1, s1, 0
	s_max_i32 vcc_lo, vcc_lo, 0
	s_max_i32 vcc_hi, vcc_hi, 0
	s_sub_i32 s1, s1, s0
	s_sub_i32 vcc_hi, vcc_hi, vcc_lo
	s_lshl_b32 s0, s0, 9
	s_lshl_b32 s1, s1, 9
	s_lshl_b32 vcc_lo, vcc_lo, 9
	s_lshl_b32 vcc_hi, vcc_hi, 9
	v_add_u32_e32 v144, s0, v152
	v_add_u32_e32 v145, vcc_lo, v153
	v_mad_i32_i24 v144, v115, s1, v144
	v_mad_i32_i24 v145, v115, vcc_hi, v145
	v_readlane_b32 s0, v244, 52
	v_readlane_b32 s1, v244, 53
	v_readlane_b32 vcc_lo, v244, 54
	v_readlane_b32 vcc_hi, v244, 55
	s_mov_b32 exec_lo, 0xffff0000
	s_mov_b32 exec_hi, 0x0
	v_mov_b32_e32 v170, s0
	v_mov_b32_e32 v176, s1
	v_mov_b32_e32 v177, vcc_lo
	v_mov_b32_e32 v191, vcc_hi
	s_mov_b64 exec, -1
	s_max_i32 s0, s0, 0
	s_max_i32 s1, s1, 0
	s_max_i32 vcc_lo, vcc_lo, 0
	s_max_i32 vcc_hi, vcc_hi, 0
	s_sub_i32 s1, s1, s0
	s_sub_i32 vcc_hi, vcc_hi, vcc_lo
	s_lshl_b32 s0, s0, 9
	s_lshl_b32 s1, s1, 9
	s_lshl_b32 vcc_lo, vcc_lo, 9
	s_lshl_b32 vcc_hi, vcc_hi, 9
	v_add_u32_e32 v146, s0, v154
	v_add_u32_e32 v147, vcc_lo, v155
	v_mad_i32_i24 v146, v115, s1, v146
	v_mad_i32_i24 v147, v115, vcc_hi, v147
	v_readlane_b32 s0, v244, 56
	v_readlane_b32 s1, v244, 57
	v_readlane_b32 vcc_lo, v244, 58
	v_readlane_b32 vcc_hi, v244, 59
	s_mov_b32 exec_lo, 0x0
	s_mov_b32 exec_hi, 0xffff
	v_mov_b32_e32 v170, s0
	v_mov_b32_e32 v176, s1
	v_mov_b32_e32 v177, vcc_lo
	v_mov_b32_e32 v191, vcc_hi
	s_mov_b64 exec, -1
	s_max_i32 s0, s0, 0
	s_max_i32 s1, s1, 0
	s_max_i32 vcc_lo, vcc_lo, 0
	s_max_i32 vcc_hi, vcc_hi, 0
	s_sub_i32 s1, s1, s0
	s_sub_i32 vcc_hi, vcc_hi, vcc_lo
	s_lshl_b32 s0, s0, 9
	s_lshl_b32 s1, s1, 9
	s_lshl_b32 vcc_lo, vcc_lo, 9
	s_lshl_b32 vcc_hi, vcc_hi, 9
	v_add_u32_e32 v172, s0, v152
	v_add_u32_e32 v173, vcc_lo, v153
	v_mad_i32_i24 v172, v115, s1, v172
	v_mad_i32_i24 v173, v115, vcc_hi, v173
	v_readlane_b32 s0, v244, 60
	v_readlane_b32 s1, v244, 61
	v_readlane_b32 vcc_lo, v244, 62
	v_readlane_b32 vcc_hi, v244, 63
	s_mov_b32 exec_lo, 0x0
	s_mov_b32 exec_hi, 0xffff0000
	v_mov_b32_e32 v170, s0
	v_mov_b32_e32 v176, s1
	v_mov_b32_e32 v177, vcc_lo
	v_mov_b32_e32 v191, vcc_hi
	s_mov_b64 exec, -1
	s_max_i32 s0, s0, 0
	s_max_i32 s1, s1, 0
	s_max_i32 vcc_lo, vcc_lo, 0
	s_max_i32 vcc_hi, vcc_hi, 0
	s_sub_i32 s1, s1, s0
	s_sub_i32 vcc_hi, vcc_hi, vcc_lo
	s_lshl_b32 s0, s0, 9
	s_lshl_b32 s1, s1, 9
	s_lshl_b32 vcc_lo, vcc_lo, 9
	s_lshl_b32 vcc_hi, vcc_hi, 9
	v_add_u32_e32 v174, s0, v154
	v_add_u32_e32 v175, vcc_lo, v155
	v_mad_i32_i24 v174, v115, s1, v174
	v_mad_i32_i24 v175, v115, vcc_hi, v175
.Latt_a_done:
	v_max_f32_e32 v82, v74, v75
	v_max_f32_e32 v73, v76, v77
	v_max3_f32 v82, v72, v80, v82
	v_max3_f32 v73, v73, v81, v82
	v_mov_b32_e32 v81, v73
	s_nop 1
	v_permlane16_swap_b32 v81, v73
	v_max_f32_e32 v73, v73, v81
	v_mov_b32_e32 v81, v73
	s_nop 1
	v_permlane32_swap_b32 v81, v73
	v_max3_f32 v73, v128, v73, v81
	v_sub_f32_e32 v72, v72, v73
	v_mul_f32_e32 v72, 0x3fb8aa3b, v72
	v_sub_f32_e32 v76, v76, v73
	v_exp_f32_e32 v82, v72
	v_sub_f32_e32 v72, v80, v73
	v_mul_f32_e32 v76, 0x3fb8aa3b, v76
	v_sub_f32_e32 v77, v77, v73
	v_mul_f32_e32 v72, 0x3fb8aa3b, v72
	v_exp_f32_e32 v76, v76
	v_mul_f32_e32 v77, 0x3fb8aa3b, v77
	v_sub_f32_e32 v78, v78, v73
	v_exp_f32_e32 v80, v72
	v_sub_f32_e32 v72, v74, v73
	v_exp_f32_e32 v77, v77
	v_mul_f32_e32 v78, 0x3fb8aa3b, v78
	v_sub_f32_e32 v79, v79, v73
	v_mul_f32_e32 v72, 0x3fb8aa3b, v72
	v_exp_f32_e32 v78, v78
	v_mul_f32_e32 v79, 0x3fb8aa3b, v79
	v_exp_f32_e32 v83, v72
	v_sub_f32_e32 v72, v75, v73
	v_exp_f32_e32 v79, v79
	v_mul_f32_e32 v72, 0x3fb8aa3b, v72
	v_exp_f32_e32 v84, v72
	v_add_f32_e32 v72, 0, v76
	v_add_f32_e32 v72, v77, v72
	v_add_f32_e32 v72, v78, v72
	v_sub_f32_e32 v81, v128, v73
	v_add_f32_e32 v72, v79, v72
	v_mul_f32_e32 v81, 0x3fb8aa3b, v81
	v_add_f32_e32 v72, v82, v72
	v_exp_f32_e32 v86, v81
	v_add_f32_e32 v72, v80, v72
	v_add_f32_e32 v72, v83, v72
	v_cvt_pk_bf16_f32 v74, v76, v77
	v_cvt_pk_bf16_f32 v75, v78, v79
	v_cvt_pk_bf16_f32 v76, v82, v80
	v_cvt_pk_bf16_f32 v77, v83, v84
	ds_read_b64_tr_b16 v[80:81], v92 offset:8192
	ds_read_b64_tr_b16 v[78:79], v92
	ds_read_b64_tr_b16 v[82:83], v93
	v_pk_mul_f32 v[70:71], v[70:71], v[86:87] op_sel_hi:[1,0]
	v_pk_mul_f32 v[68:69], v[68:69], v[86:87] op_sel_hi:[1,0]
	v_add_f32_e32 v72, v84, v72
	ds_read_b64_tr_b16 v[84:85], v93 offset:8192
	s_waitcnt lgkmcnt(2)
	v_mfma_f32_16x16x32_bf16 v[68:71], v[78:81], v[74:77], v[68:71]
	ds_read_b64_tr_b16 v[78:79], v94
	ds_read_b64_tr_b16 v[80:81], v94 offset:8192
	v_pk_mul_f32 v[66:67], v[66:67], v[86:87] op_sel_hi:[1,0]
	v_pk_mul_f32 v[64:65], v[64:65], v[86:87] op_sel_hi:[1,0]
	v_pk_mul_f32 v[62:63], v[62:63], v[86:87] op_sel_hi:[1,0]
	v_pk_mul_f32 v[60:61], v[60:61], v[86:87] op_sel_hi:[1,0]
	s_waitcnt lgkmcnt(0)
	v_mfma_f32_16x16x32_bf16 v[64:67], v[78:81], v[74:77], v[64:67]
	ds_read_b64_tr_b16 v[78:79], v95
	ds_read_b64_tr_b16 v[80:81], v95 offset:8192
	v_pk_mul_f32 v[26:27], v[26:27], v[86:87] op_sel_hi:[1,0]
	v_pk_mul_f32 v[24:25], v[24:25], v[86:87] op_sel_hi:[1,0]
	s_waitcnt lgkmcnt(0)
	v_mfma_f32_16x16x32_bf16 v[60:63], v[78:81], v[74:77], v[60:63]
	v_mul_f32_e64 v58, v58, v86
	v_mul_f32_e64 v59, v59, v86
	v_pk_mul_f32 v[56:57], v[56:57], v[86:87] op_sel_hi:[1,0]
	v_pk_mul_f32 v[50:51], v[50:51], v[86:87] op_sel_hi:[1,0]
	v_mfma_f32_16x16x32_bf16 v[24:27], v[82:85], v[74:77], v[24:27]
	ds_read_b64_tr_b16 v[80:81], v96 offset:8192
	ds_read_b64_tr_b16 v[78:79], v96
	ds_read_b64_tr_b16 v[82:83], v97
	ds_read_b64_tr_b16 v[84:85], v97 offset:8192
	v_pk_mul_f32 v[48:49], v[48:49], v[86:87] op_sel_hi:[1,0]
	s_waitcnt lgkmcnt(2)
	v_mfma_f32_16x16x32_bf16 v[56:59], v[78:81], v[74:77], v[56:59]
	ds_read_b64_tr_b16 v[78:79], v98
	ds_read_b64_tr_b16 v[80:81], v98 offset:8192
	v_pk_mul_f32 v[54:55], v[54:55], v[86:87] op_sel_hi:[1,0]
	v_pk_mul_f32 v[52:53], v[52:53], v[86:87] op_sel_hi:[1,0]
	s_waitcnt lgkmcnt(0)
	v_mfma_f32_16x16x32_bf16 v[48:51], v[78:81], v[74:77], v[48:51]
	ds_read_b64_tr_b16 v[78:79], v99
	ds_read_b64_tr_b16 v[80:81], v99 offset:8192
	v_pk_mul_f32 v[46:47], v[46:47], v[86:87] op_sel_hi:[1,0]
	v_pk_mul_f32 v[44:45], v[44:45], v[86:87] op_sel_hi:[1,0]
	v_mfma_f32_16x16x32_bf16 v[52:55], v[82:85], v[74:77], v[52:55]
	v_mul_f32_e64 v42, v42, v86
	v_mul_f32_e64 v43, v43, v86
	v_pk_mul_f32 v[40:41], v[40:41], v[86:87] op_sel_hi:[1,0]
	v_pk_mul_f32 v[22:23], v[22:23], v[86:87] op_sel_hi:[1,0]
	s_waitcnt lgkmcnt(0)
	v_mfma_f32_16x16x32_bf16 v[44:47], v[78:81], v[74:77], v[44:47]
	ds_read_b64_tr_b16 v[80:81], v92 offset:8448
	ds_read_b64_tr_b16 v[78:79], v92 offset:256
	ds_read_b64_tr_b16 v[82:83], v93 offset:256
	ds_read_b64_tr_b16 v[84:85], v93 offset:8448
	v_pk_mul_f32 v[20:21], v[20:21], v[86:87] op_sel_hi:[1,0]
	s_waitcnt lgkmcnt(2)
	v_mfma_f32_16x16x32_bf16 v[40:43], v[78:81], v[74:77], v[40:43]
	ds_read_b64_tr_b16 v[78:79], v94 offset:256
	ds_read_b64_tr_b16 v[80:81], v94 offset:8448
	v_pk_mul_f32 v[30:31], v[30:31], v[86:87] op_sel_hi:[1,0]
	v_pk_mul_f32 v[28:29], v[28:29], v[86:87] op_sel_hi:[1,0]
	s_waitcnt lgkmcnt(0)
	v_mfma_f32_16x16x32_bf16 v[20:23], v[78:81], v[74:77], v[20:23]
	ds_read_b64_tr_b16 v[78:79], v95 offset:256
	ds_read_b64_tr_b16 v[80:81], v95 offset:8448
	v_pk_mul_f32 v[18:19], v[18:19], v[86:87] op_sel_hi:[1,0]
	v_pk_mul_f32 v[16:17], v[16:17], v[86:87] op_sel_hi:[1,0]
	v_mfma_f32_16x16x32_bf16 v[28:31], v[82:85], v[74:77], v[28:31]
	v_mul_f32_e64 v14, v14, v86
	v_mul_f32_e64 v15, v15, v86
	v_pk_mul_f32 v[12:13], v[12:13], v[86:87] op_sel_hi:[1,0]
	v_pk_mul_f32 v[6:7], v[6:7], v[86:87] op_sel_hi:[1,0]
	s_waitcnt lgkmcnt(0)
	v_mfma_f32_16x16x32_bf16 v[16:19], v[78:81], v[74:77], v[16:19]
	ds_read_b64_tr_b16 v[80:81], v96 offset:8448
	ds_read_b64_tr_b16 v[78:79], v96 offset:256
	ds_read_b64_tr_b16 v[82:83], v97 offset:256
	ds_read_b64_tr_b16 v[84:85], v97 offset:8448
	v_pk_mul_f32 v[4:5], v[4:5], v[86:87] op_sel_hi:[1,0]
	s_waitcnt lgkmcnt(2)
	v_mfma_f32_16x16x32_bf16 v[12:15], v[78:81], v[74:77], v[12:15]
	ds_read_b64_tr_b16 v[78:79], v98 offset:256
	ds_read_b64_tr_b16 v[80:81], v98 offset:8448
	v_pk_mul_f32 v[10:11], v[10:11], v[86:87] op_sel_hi:[1,0]
	v_pk_mul_f32 v[8:9], v[8:9], v[86:87] op_sel_hi:[1,0]
	s_waitcnt lgkmcnt(0)
	v_mfma_f32_16x16x32_bf16 v[4:7], v[78:81], v[74:77], v[4:7]
	ds_read_b64_tr_b16 v[78:79], v99 offset:256
	ds_read_b64_tr_b16 v[80:81], v99 offset:8448
	v_pk_mul_f32 v[2:3], v[2:3], v[86:87] op_sel_hi:[1,0]
	v_pk_mul_f32 v[0:1], v[0:1], v[86:87] op_sel_hi:[1,0]
	v_mfma_f32_16x16x32_bf16 v[8:11], v[82:85], v[74:77], v[8:11]
	s_waitcnt lgkmcnt(0)
	v_fmac_f32_e32 v72, v129, v86
	s_waitcnt lgkmcnt(0)
	v_mfma_f32_16x16x32_bf16 v[0:3], v[78:81], v[74:77], v[0:3]
	v_mov_b32_e32 v128, v73
	s_add_i32 s30, s30, 1
	s_add_i32 s28, s28, 32
	s_cmp_eq_u32 s30, 8
	s_cbranch_scc0 .LBB0_136
	ds_bpermute_b32 v73, v113, v72
	v_mov_b32_e32 v124, v123
	v_mov_b32_e32 v125, v122
	v_mov_b32_e32 v126, v121
	v_mov_b32_e32 v127, v120
	s_waitcnt lgkmcnt(0)
	v_add_f32_e32 v72, v72, v73
	ds_bpermute_b32 v73, v114, v72
	s_mov_b32 s2, s25
	s_waitcnt lgkmcnt(0)
	v_add_f32_e32 v72, v72, v73
	v_div_scale_f32 v73, s[0:1], v72, v72, 1.0
	v_rcp_f32_e32 v74, v73
	s_lshl_b64 s[0:1], s[76:77], 13
	s_mov_b32 s76, s38
	v_fma_f32 v75, -v73, v74, 1.0
	v_fmac_f32_e32 v74, v75, v74
	v_div_scale_f32 v75, vcc, 1.0, v72, 1.0
	v_mul_f32_e32 v76, v75, v74
	v_fma_f32 v77, -v73, v76, v75
	v_fmac_f32_e32 v76, v77, v74
	v_fma_f32 v73, -v73, v76, v75
	v_div_fmas_f32 v73, v73, v74, v76
	v_div_fixup_f32 v72, v73, v72, 1.0
	v_pk_mul_f32 v[24:25], v[24:25], v[72:73] op_sel_hi:[1,0]
	v_pk_mul_f32 v[26:27], v[26:27], v[72:73] op_sel_hi:[1,0]
	v_lshl_add_u64 v[74:75], v[104:105], 0, s[0:1]
	v_cvt_pk_bf16_f32 v24, v24, v25
	v_cvt_pk_bf16_f32 v25, v26, v27
	global_store_dwordx2 v[74:75], v[24:25], off offset:32
	v_pk_mul_f32 v[24:25], v[64:65], v[72:73] op_sel_hi:[1,0]
	v_pk_mul_f32 v[26:27], v[66:67], v[72:73] op_sel_hi:[1,0]
	v_cvt_pk_bf16_f32 v24, v24, v25
	v_cvt_pk_bf16_f32 v25, v26, v27
	global_store_dwordx2 v[74:75], v[24:25], off offset:64
	v_pk_mul_f32 v[24:25], v[60:61], v[72:73] op_sel_hi:[1,0]
	v_pk_mul_f32 v[26:27], v[62:63], v[72:73] op_sel_hi:[1,0]
	v_cvt_pk_bf16_f32 v24, v24, v25
	v_cvt_pk_bf16_f32 v25, v26, v27
	global_store_dwordx2 v[74:75], v[24:25], off offset:96
	v_pk_mul_f32 v[24:25], v[56:57], v[72:73] op_sel_hi:[1,0]
	v_pk_mul_f32 v[26:27], v[58:59], v[72:73] op_sel_hi:[1,0]
	v_cvt_pk_bf16_f32 v24, v24, v25
	v_cvt_pk_bf16_f32 v25, v26, v27
	global_store_dwordx2 v[74:75], v[24:25], off offset:128
	v_pk_mul_f32 v[24:25], v[52:53], v[72:73] op_sel_hi:[1,0]
	v_pk_mul_f32 v[26:27], v[54:55], v[72:73] op_sel_hi:[1,0]
	v_cvt_pk_bf16_f32 v24, v24, v25
	v_cvt_pk_bf16_f32 v25, v26, v27
	global_store_dwordx2 v[74:75], v[24:25], off offset:160
	v_pk_mul_f32 v[24:25], v[48:49], v[72:73] op_sel_hi:[1,0]
	v_pk_mul_f32 v[26:27], v[50:51], v[72:73] op_sel_hi:[1,0]
	v_cvt_pk_bf16_f32 v24, v24, v25
	v_cvt_pk_bf16_f32 v25, v26, v27
	global_store_dwordx2 v[74:75], v[24:25], off offset:192
	v_pk_mul_f32 v[24:25], v[44:45], v[72:73] op_sel_hi:[1,0]
	v_pk_mul_f32 v[26:27], v[46:47], v[72:73] op_sel_hi:[1,0]
	v_cvt_pk_bf16_f32 v24, v24, v25
	v_cvt_pk_bf16_f32 v25, v26, v27
	global_store_dwordx2 v[74:75], v[24:25], off offset:224
	v_pk_mul_f32 v[24:25], v[40:41], v[72:73] op_sel_hi:[1,0]
	v_pk_mul_f32 v[26:27], v[42:43], v[72:73] op_sel_hi:[1,0]
	v_cvt_pk_bf16_f32 v24, v24, v25
	v_cvt_pk_bf16_f32 v25, v26, v27
	v_pk_mul_f32 v[68:69], v[68:69], v[72:73] op_sel_hi:[1,0]
	v_pk_mul_f32 v[70:71], v[70:71], v[72:73] op_sel_hi:[1,0]
	global_store_dwordx2 v[74:75], v[24:25], off offset:256
	v_pk_mul_f32 v[24:25], v[28:29], v[72:73] op_sel_hi:[1,0]
	v_pk_mul_f32 v[26:27], v[30:31], v[72:73] op_sel_hi:[1,0]
	v_pk_mul_f32 v[20:21], v[20:21], v[72:73] op_sel_hi:[1,0]
	v_pk_mul_f32 v[22:23], v[22:23], v[72:73] op_sel_hi:[1,0]
	v_pk_mul_f32 v[16:17], v[16:17], v[72:73] op_sel_hi:[1,0]
	v_pk_mul_f32 v[18:19], v[18:19], v[72:73] op_sel_hi:[1,0]
	v_pk_mul_f32 v[12:13], v[12:13], v[72:73] op_sel_hi:[1,0]
	v_pk_mul_f32 v[14:15], v[14:15], v[72:73] op_sel_hi:[1,0]
	v_pk_mul_f32 v[8:9], v[8:9], v[72:73] op_sel_hi:[1,0]
	v_pk_mul_f32 v[10:11], v[10:11], v[72:73] op_sel_hi:[1,0]
	v_pk_mul_f32 v[4:5], v[4:5], v[72:73] op_sel_hi:[1,0]
	v_pk_mul_f32 v[6:7], v[6:7], v[72:73] op_sel_hi:[1,0]
	v_pk_mul_f32 v[0:1], v[0:1], v[72:73] op_sel_hi:[1,0]
	v_pk_mul_f32 v[2:3], v[2:3], v[72:73] op_sel_hi:[1,0]
	v_cvt_pk_bf16_f32 v68, v68, v69
	v_cvt_pk_bf16_f32 v69, v70, v71
	v_cvt_pk_bf16_f32 v24, v24, v25
	v_cvt_pk_bf16_f32 v25, v26, v27
	v_cvt_pk_bf16_f32 v20, v20, v21
	v_cvt_pk_bf16_f32 v21, v22, v23
	v_cvt_pk_bf16_f32 v16, v16, v17
	v_cvt_pk_bf16_f32 v17, v18, v19
	v_cvt_pk_bf16_f32 v12, v12, v13
	v_cvt_pk_bf16_f32 v13, v14, v15
	v_cvt_pk_bf16_f32 v8, v8, v9
	v_cvt_pk_bf16_f32 v9, v10, v11
	v_cvt_pk_bf16_f32 v4, v4, v5
	v_cvt_pk_bf16_f32 v5, v6, v7
	v_cvt_pk_bf16_f32 v0, v0, v1
	v_cvt_pk_bf16_f32 v1, v2, v3
	s_and_b64 vcc, exec, s[40:41]
	global_store_dwordx2 v[74:75], v[68:69], off
	global_store_dwordx2 v[74:75], v[24:25], off offset:288
	global_store_dwordx2 v[74:75], v[20:21], off offset:320
	global_store_dwordx2 v[74:75], v[16:17], off offset:352
	global_store_dwordx2 v[74:75], v[12:13], off offset:384
	global_store_dwordx2 v[74:75], v[8:9], off offset:416
	global_store_dwordx2 v[74:75], v[4:5], off offset:448
	global_store_dwordx2 v[74:75], v[0:1], off offset:480
	s_cbranch_vccz .LBB0_128
